# adds: in the FFN gate/up K-loop the last 2 of the 6 LDS-DMA loads of phases 2 and 4 are issued between the two 16-MFMA groups of the same phase (vmcnt 8 -> 6 there)
# baseline (speedup 1.0000x reference)
; #define PG8_STAGE(bufoff, gbase, voff) do { _Pragma("unroll") for (int _i = 0; _i < 2; ++_i) \
;         __builtin_amdgcn_global_load_lds((const unsigned*)((const char*)(gbase) + (voff)[_i]), (LAS unsigned*)(lds + (bufoff) + ldsw + _i * 8192), 16, 0, 0); } while (0)
; #define PG8_LDA(dst, b, h) do { _Pragma("unroll") for (int m = 0; m < 4; ++m) _Pragma("unroll") for (int k = 0; k < 2; ++k) dst[m][k] = *(const LAS bf16x8*)(lds + PG8_SA(b, h) + aoff + m * 2048 + k * 1024); } while (0)
; #define PG8_LDB(dst, b, h) do { _Pragma("unroll") for (int n = 0; n < 2; ++n) _Pragma("unroll") for (int k = 0; k < 2; ++k) dst[n][k] = *(const LAS bf16x8*)(lds + PG8_SB(b, h) + boff + n * 2048 + k * 1024); } while (0)
; #define PG8_MMA(ai, bj, At, Bt) do { __builtin_amdgcn_s_setprio(1); _Pragma("unroll") for (int m = 0; m < 4; ++m) _Pragma("unroll") for (int n = 0; n < 2; ++n) _Pragma("unroll") for (int k = 0; k < 2; ++k) \
;         acc[ai][bj][m][n] = __builtin_amdgcn_mfma_f32_16x16x32_bf16(Bt[n][k], At[m][k], acc[ai][bj][m][n], 0, 0, 0); __builtin_amdgcn_s_setprio(0); } while (0)
; #define PG8_WAIT_V(n) asm volatile("s_waitcnt vmcnt(" #n ")" ::: "memory")
; #define PG8_WAIT_L(n) asm volatile("s_waitcnt lgkmcnt(" #n ")" ::: "memory")
; #define PG8_BAR __builtin_amdgcn_s_barrier()
; template <class Epi, class Sched>
; __device__ __forceinline__ void gemm_phase(LAS unsigned char* lds, const Gemm g, const Sched& S, const Epi& E) {
;     ...
;         const char* nA = has_next ? (const char*)g.A + (size_t)nxt.pm * tstepA + (size_t)nxt.pn * apn : cA; const char* nB = has_next ? (const char*)g.Bt + (size_t)nxt.pn * tstepB : cB;
;         for (int t = 0; t < nt; t += 2) {
;             const bool last = (t == nt - 2);
;             const char* a1 = cA + (size_t)(t + 1) * kstep;
;             const char* a2 = last ? nA : cA + (size_t)(t + 2) * kstep; const char* b2 = last ? nB : cB + (size_t)(t + 2) * kstep;
;             const char* a3 = a2 + kstep; const char* b3 = b2 + kstep;
;             PG8_LDB(B0, 0, 0); PG8_LDB(B1, 0, 1); PG8_SCHED; PG8_LDA(At, 0, 0); PG8_STAGE(PG8_SA(1, 1), a1 + hstepA, voffA);
;             PG8_WAIT_V(8); PG8_WAIT_L(0); PG8_BAR; PG8_MMA(0, 0, At, B0); PG8_MMA(0, 1, At, B1); PG8_BAR; PG8_SCHED;
;             PG8_LDA(At, 0, 1); PG8_STAGE(PG8_SB(0, 0), b2, voffB); PG8_STAGE(PG8_SB(0, 1), b2 + hstepB, voffB); PG8_STAGE(PG8_SA(0, 0), a2, voffA);
.LBB0_718:
	s_add_u32 s0, s44, 0xfffc0080
	s_addc_u32 s6, s45, -1
	s_add_i32 s26, 0, 0x10000
	s_cmp_eq_u32 s55, 12
	s_cselect_b32 s15, s23, s6
	s_cselect_b32 s14, s53, s0
	v_add_u32_e32 v153, s26, v148
	s_cselect_b32 s7, s19, s47
	s_cselect_b32 s6, s54, s46
	s_add_i32 s0, 0, 0x14000
	ds_read_b128 v[142:145], v153
	ds_read_b128 v[154:157], v153 offset:1024
	ds_read_b128 v[162:165], v153 offset:2048
	ds_read_b128 v[166:169], v153 offset:3072
	v_add_u32_e32 v153, s0, v148
	ds_read_b128 v[170:173], v153
	ds_read_b128 v[174:177], v153 offset:1024
	ds_read_b128 v[190:193], v153 offset:2048
	ds_read_b128 v[196:199], v153 offset:3072
	v_lshl_add_u64 v[158:159], s[44:45], 0, v[138:139]
	s_add_i32 m0, s49, 0xc000
	ds_read_b128 v[200:203], v152
	ds_read_b128 v[204:207], v152 offset:1024
	ds_read_b128 v[208:211], v152 offset:2048
	ds_read_b128 v[212:215], v152 offset:3072
	ds_read_b128 v[216:219], v152 offset:4096
	ds_read_b128 v[220:223], v152 offset:5120
	ds_read_b128 v[224:227], v152 offset:6144
	ds_read_b128 v[228:231], v152 offset:7168
	global_load_lds_dwordx4 v[158:159], off
	v_lshl_add_u64 v[158:159], s[44:45], 0, v[140:141]
	s_add_i32 m0, s49, 0xe000
	s_nop 0
	global_load_lds_dwordx4 v[158:159], off
	s_waitcnt vmcnt(8)
	s_waitcnt lgkmcnt(0)
	s_barrier
	s_waitcnt lgkmcnt(0)
	v_mfma_f32_16x16x32_bf16 v[128:131], v[142:145], v[200:203], v[128:131]
	v_mfma_f32_16x16x32_bf16 v[124:127], v[162:165], v[200:203], v[124:127]
	v_mfma_f32_16x16x32_bf16 v[112:115], v[142:145], v[208:211], v[112:115]
	v_mfma_f32_16x16x32_bf16 v[108:111], v[162:165], v[208:211], v[108:111]
	v_mfma_f32_16x16x32_bf16 v[96:99], v[142:145], v[216:219], v[96:99]
	v_mfma_f32_16x16x32_bf16 v[92:95], v[162:165], v[216:219], v[92:95]
	v_mfma_f32_16x16x32_bf16 v[80:83], v[142:145], v[224:227], v[80:83]
	v_mfma_f32_16x16x32_bf16 v[76:79], v[162:165], v[224:227], v[76:79]
	v_mfma_f32_16x16x32_bf16 v[128:131], v[154:157], v[204:207], v[128:131]
	v_mfma_f32_16x16x32_bf16 v[124:127], v[166:169], v[204:207], v[124:127]
	v_mfma_f32_16x16x32_bf16 v[112:115], v[154:157], v[212:215], v[112:115]
	v_mfma_f32_16x16x32_bf16 v[108:111], v[166:169], v[212:215], v[108:111]
	v_mfma_f32_16x16x32_bf16 v[96:99], v[154:157], v[220:223], v[96:99]
	v_mfma_f32_16x16x32_bf16 v[92:95], v[166:169], v[220:223], v[92:95]
	v_mfma_f32_16x16x32_bf16 v[80:83], v[154:157], v[228:231], v[80:83]
	v_mfma_f32_16x16x32_bf16 v[76:79], v[166:169], v[228:231], v[76:79]
	v_mfma_f32_16x16x32_bf16 v[120:123], v[170:173], v[200:203], v[120:123]
	v_mfma_f32_16x16x32_bf16 v[116:119], v[190:193], v[200:203], v[116:119]
	v_mfma_f32_16x16x32_bf16 v[104:107], v[170:173], v[208:211], v[104:107]
	v_mfma_f32_16x16x32_bf16 v[100:103], v[190:193], v[208:211], v[100:103]
	v_mfma_f32_16x16x32_bf16 v[88:91], v[170:173], v[216:219], v[88:91]
	v_mfma_f32_16x16x32_bf16 v[84:87], v[190:193], v[216:219], v[84:87]
	v_mfma_f32_16x16x32_bf16 v[72:75], v[170:173], v[224:227], v[72:75]
	v_mfma_f32_16x16x32_bf16 v[68:71], v[190:193], v[224:227], v[68:71]
	v_mfma_f32_16x16x32_bf16 v[120:123], v[174:177], v[204:207], v[120:123]
	v_mfma_f32_16x16x32_bf16 v[116:119], v[196:199], v[204:207], v[116:119]
	v_mfma_f32_16x16x32_bf16 v[104:107], v[174:177], v[212:215], v[104:107]
	v_mfma_f32_16x16x32_bf16 v[100:103], v[196:199], v[212:215], v[100:103]
	v_mfma_f32_16x16x32_bf16 v[88:91], v[174:177], v[220:223], v[88:91]
	v_mfma_f32_16x16x32_bf16 v[84:87], v[196:199], v[220:223], v[84:87]
	v_mfma_f32_16x16x32_bf16 v[72:75], v[174:177], v[228:231], v[72:75]
	v_mfma_f32_16x16x32_bf16 v[68:71], v[196:199], v[228:231], v[68:71]
	s_barrier
	s_add_i32 s26, s26, s20
	v_lshl_add_u64 v[158:159], s[6:7], 0, v[160:161]
	s_mov_b32 m0, s26
	ds_read_b128 v[200:203], v152 offset:16384
	ds_read_b128 v[204:207], v152 offset:17408
	ds_read_b128 v[208:211], v152 offset:18432
	ds_read_b128 v[212:215], v152 offset:19456
	ds_read_b128 v[216:219], v152 offset:20480
	ds_read_b128 v[220:223], v152 offset:21504
	ds_read_b128 v[224:227], v152 offset:22528
	ds_read_b128 v[228:231], v152 offset:23552
	global_load_lds_dwordx4 v[158:159], off
	s_add_i32 m0, s26, 0x2000
	s_add_u32 s56, s6, 0x40000
	v_lshl_add_u64 v[232:233], s[6:7], 0, v[136:137]
	s_addc_u32 s57, s7, 0
	s_add_i32 s0, s0, s20
	global_load_lds_dwordx4 v[232:233], off
	v_lshl_add_u64 v[234:235], s[56:57], 0, v[160:161]
	s_mov_b32 m0, s0
	v_lshl_add_u64 v[236:237], s[14:15], 0, v[134:135]
	global_load_lds_dwordx4 v[234:235], off
	v_lshl_add_u64 v[234:235], s[56:57], 0, v[136:137]
	s_add_i32 m0, s0, 0x2000
	s_nop 0
	global_load_lds_dwordx4 v[234:235], off
	v_lshl_add_u64 v[234:235], s[14:15], 0, v[132:133]
	s_waitcnt vmcnt(6)
	s_waitcnt lgkmcnt(0)
	s_barrier
; #define PG8_STAGE(bufoff, gbase, voff) do { _Pragma("unroll") for (int _i = 0; _i < 2; ++_i) \
;         __builtin_amdgcn_global_load_lds((const unsigned*)((const char*)(gbase) + (voff)[_i]), (LAS unsigned*)(lds + (bufoff) + ldsw + _i * 8192), 16, 0, 0); } while (0)
; #define PG8_LDA(dst, b, h) do { _Pragma("unroll") for (int m = 0; m < 4; ++m) _Pragma("unroll") for (int k = 0; k < 2; ++k) dst[m][k] = *(const LAS bf16x8*)(lds + PG8_SA(b, h) + aoff + m * 2048 + k * 1024); } while (0)
; #define PG8_LDB(dst, b, h) do { _Pragma("unroll") for (int n = 0; n < 2; ++n) _Pragma("unroll") for (int k = 0; k < 2; ++k) dst[n][k] = *(const LAS bf16x8*)(lds + PG8_SB(b, h) + boff + n * 2048 + k * 1024); } while (0)
; #define PG8_MMA(ai, bj, At, Bt) do { __builtin_amdgcn_s_setprio(1); _Pragma("unroll") for (int m = 0; m < 4; ++m) _Pragma("unroll") for (int n = 0; n < 2; ++n) _Pragma("unroll") for (int k = 0; k < 2; ++k) \
;         acc[ai][bj][m][n] = __builtin_amdgcn_mfma_f32_16x16x32_bf16(Bt[n][k], At[m][k], acc[ai][bj][m][n], 0, 0, 0); __builtin_amdgcn_s_setprio(0); } while (0)
; #define PG8_WAIT_V(n) asm volatile("s_waitcnt vmcnt(" #n ")" ::: "memory")
; #define PG8_WAIT_L(n) asm volatile("s_waitcnt lgkmcnt(" #n ")" ::: "memory")
; #define PG8_BAR __builtin_amdgcn_s_barrier()
; #define PG8_SCHED __builtin_amdgcn_sched_barrier(0)
; template <class Epi, class Sched>
; __device__ __forceinline__ void gemm_phase(LAS unsigned char* lds, const Gemm g, const Sched& S, const Epi& E) {
;     ...
;             PG8_WAIT_V(8); PG8_WAIT_L(0); PG8_BAR; PG8_MMA(1, 0, At, B0); PG8_MMA(1, 1, At, B1); PG8_BAR; PG8_SCHED;
;             PG8_LDB(B0, 1, 0); PG8_LDB(B1, 1, 1); PG8_SCHED; PG8_LDA(At, 1, 0); PG8_STAGE(PG8_SA(0, 1), a2 + hstepA, voffA);
;             PG8_WAIT_V(8); PG8_WAIT_L(0); PG8_BAR; PG8_MMA(0, 0, At, B0); PG8_MMA(0, 1, At, B1); PG8_BAR; PG8_SCHED;
	s_waitcnt lgkmcnt(0)
	v_mfma_f32_16x16x32_bf16 v[64:67], v[142:145], v[200:203], v[64:67]
	v_mfma_f32_16x16x32_bf16 v[60:63], v[162:165], v[200:203], v[60:63]
	v_mfma_f32_16x16x32_bf16 v[48:51], v[142:145], v[208:211], v[48:51]
	v_mfma_f32_16x16x32_bf16 v[44:47], v[162:165], v[208:211], v[44:47]
	v_mfma_f32_16x16x32_bf16 v[32:35], v[142:145], v[216:219], v[32:35]
	v_mfma_f32_16x16x32_bf16 v[28:31], v[162:165], v[216:219], v[28:31]
	v_mfma_f32_16x16x32_bf16 v[16:19], v[142:145], v[224:227], v[16:19]
	v_mfma_f32_16x16x32_bf16 v[12:15], v[162:165], v[224:227], v[12:15]
	v_mfma_f32_16x16x32_bf16 v[64:67], v[154:157], v[204:207], v[64:67]
	v_mfma_f32_16x16x32_bf16 v[60:63], v[166:169], v[204:207], v[60:63]
	v_mfma_f32_16x16x32_bf16 v[48:51], v[154:157], v[212:215], v[48:51]
	v_mfma_f32_16x16x32_bf16 v[44:47], v[166:169], v[212:215], v[44:47]
	v_mfma_f32_16x16x32_bf16 v[32:35], v[154:157], v[220:223], v[32:35]
	v_mfma_f32_16x16x32_bf16 v[28:31], v[166:169], v[220:223], v[28:31]
	v_mfma_f32_16x16x32_bf16 v[16:19], v[154:157], v[228:231], v[16:19]
	v_mfma_f32_16x16x32_bf16 v[12:15], v[166:169], v[228:231], v[12:15]
	s_mov_b32 m0, s49
	s_nop 0
	global_load_lds_dwordx4 v[234:235], off
	s_mov_b32 m0, s50
	s_nop 0
	global_load_lds_dwordx4 v[236:237], off
	v_mfma_f32_16x16x32_bf16 v[56:59], v[170:173], v[200:203], v[56:59]
	v_mfma_f32_16x16x32_bf16 v[52:55], v[190:193], v[200:203], v[52:55]
	v_mfma_f32_16x16x32_bf16 v[40:43], v[170:173], v[208:211], v[40:43]
	v_mfma_f32_16x16x32_bf16 v[36:39], v[190:193], v[208:211], v[36:39]
	v_mfma_f32_16x16x32_bf16 v[24:27], v[170:173], v[216:219], v[24:27]
	v_mfma_f32_16x16x32_bf16 v[20:23], v[190:193], v[216:219], v[20:23]
	v_mfma_f32_16x16x32_bf16 v[8:11], v[170:173], v[224:227], v[8:11]
	v_mfma_f32_16x16x32_bf16 v[4:7], v[190:193], v[224:227], v[4:7]
	v_mfma_f32_16x16x32_bf16 v[56:59], v[174:177], v[204:207], v[56:59]
	v_mfma_f32_16x16x32_bf16 v[52:55], v[196:199], v[204:207], v[52:55]
	v_mfma_f32_16x16x32_bf16 v[40:43], v[174:177], v[212:215], v[40:43]
	v_mfma_f32_16x16x32_bf16 v[36:39], v[196:199], v[212:215], v[36:39]
	v_mfma_f32_16x16x32_bf16 v[24:27], v[174:177], v[220:223], v[24:27]
	v_mfma_f32_16x16x32_bf16 v[20:23], v[196:199], v[220:223], v[20:23]
	v_mfma_f32_16x16x32_bf16 v[8:11], v[174:177], v[228:231], v[8:11]
	v_mfma_f32_16x16x32_bf16 v[4:7], v[196:199], v[228:231], v[4:7]
	s_barrier
	s_add_i32 s0, 0, 0x18000
	v_add_u32_e32 v153, s0, v148
	s_add_i32 s26, 0, 0x1c000
	ds_read_b128 v[142:145], v153
	ds_read_b128 v[154:157], v153 offset:1024
	ds_read_b128 v[162:165], v153 offset:2048
	ds_read_b128 v[166:169], v153 offset:3072
	v_add_u32_e32 v153, s26, v148
	ds_read_b128 v[170:173], v153
	ds_read_b128 v[174:177], v153 offset:1024
	ds_read_b128 v[190:193], v153 offset:2048
	ds_read_b128 v[196:199], v153 offset:3072
	s_add_u32 s14, s14, 0x40000
	s_addc_u32 s15, s15, 0
	s_mov_b32 m0, s51
	v_lshl_add_u64 v[238:239], s[14:15], 0, v[132:133]
	ds_read_b128 v[200:203], v152 offset:32768
	ds_read_b128 v[204:207], v152 offset:33792
	ds_read_b128 v[208:211], v152 offset:34816
	ds_read_b128 v[212:215], v152 offset:35840
	ds_read_b128 v[216:219], v152 offset:36864
	ds_read_b128 v[220:223], v152 offset:37888
	ds_read_b128 v[224:227], v152 offset:38912
	ds_read_b128 v[228:231], v152 offset:39936
	global_load_lds_dwordx4 v[238:239], off
	v_lshl_add_u64 v[238:239], s[14:15], 0, v[134:135]
	s_mov_b32 m0, s52
	s_nop 0
	global_load_lds_dwordx4 v[238:239], off
	s_waitcnt vmcnt(8)
	s_waitcnt lgkmcnt(0)
	s_barrier
	s_waitcnt lgkmcnt(0)
	v_mfma_f32_16x16x32_bf16 v[128:131], v[142:145], v[200:203], v[128:131]
	v_mfma_f32_16x16x32_bf16 v[124:127], v[162:165], v[200:203], v[124:127]
	v_mfma_f32_16x16x32_bf16 v[112:115], v[142:145], v[208:211], v[112:115]
	v_mfma_f32_16x16x32_bf16 v[108:111], v[162:165], v[208:211], v[108:111]
	v_mfma_f32_16x16x32_bf16 v[96:99], v[142:145], v[216:219], v[96:99]
	v_mfma_f32_16x16x32_bf16 v[92:95], v[162:165], v[216:219], v[92:95]
	v_mfma_f32_16x16x32_bf16 v[80:83], v[142:145], v[224:227], v[80:83]
	v_mfma_f32_16x16x32_bf16 v[76:79], v[162:165], v[224:227], v[76:79]
	v_mfma_f32_16x16x32_bf16 v[128:131], v[154:157], v[204:207], v[128:131]
	v_mfma_f32_16x16x32_bf16 v[124:127], v[166:169], v[204:207], v[124:127]
	v_mfma_f32_16x16x32_bf16 v[112:115], v[154:157], v[212:215], v[112:115]
	v_mfma_f32_16x16x32_bf16 v[108:111], v[166:169], v[212:215], v[108:111]
	v_mfma_f32_16x16x32_bf16 v[96:99], v[154:157], v[220:223], v[96:99]
	v_mfma_f32_16x16x32_bf16 v[92:95], v[166:169], v[220:223], v[92:95]
	v_mfma_f32_16x16x32_bf16 v[80:83], v[154:157], v[228:231], v[80:83]
	v_mfma_f32_16x16x32_bf16 v[76:79], v[166:169], v[228:231], v[76:79]
	v_mfma_f32_16x16x32_bf16 v[120:123], v[170:173], v[200:203], v[120:123]
	v_mfma_f32_16x16x32_bf16 v[116:119], v[190:193], v[200:203], v[116:119]
	v_mfma_f32_16x16x32_bf16 v[104:107], v[170:173], v[208:211], v[104:107]
	v_mfma_f32_16x16x32_bf16 v[100:103], v[190:193], v[208:211], v[100:103]
	v_mfma_f32_16x16x32_bf16 v[88:91], v[170:173], v[216:219], v[88:91]
	v_mfma_f32_16x16x32_bf16 v[84:87], v[190:193], v[216:219], v[84:87]
	v_mfma_f32_16x16x32_bf16 v[72:75], v[170:173], v[224:227], v[72:75]
	v_mfma_f32_16x16x32_bf16 v[68:71], v[190:193], v[224:227], v[68:71]
	v_mfma_f32_16x16x32_bf16 v[120:123], v[174:177], v[204:207], v[120:123]
	v_mfma_f32_16x16x32_bf16 v[116:119], v[196:199], v[204:207], v[116:119]
	v_mfma_f32_16x16x32_bf16 v[104:107], v[174:177], v[212:215], v[104:107]
	v_mfma_f32_16x16x32_bf16 v[100:103], v[196:199], v[212:215], v[100:103]
	v_mfma_f32_16x16x32_bf16 v[88:91], v[174:177], v[220:223], v[88:91]
	v_mfma_f32_16x16x32_bf16 v[84:87], v[196:199], v[220:223], v[84:87]
	v_mfma_f32_16x16x32_bf16 v[72:75], v[174:177], v[228:231], v[72:75]
	v_mfma_f32_16x16x32_bf16 v[68:71], v[196:199], v[228:231], v[68:71]
	s_barrier
; #define PG8_STAGE(bufoff, gbase, voff) do { _Pragma("unroll") for (int _i = 0; _i < 2; ++_i) \
;         __builtin_amdgcn_global_load_lds((const unsigned*)((const char*)(gbase) + (voff)[_i]), (LAS unsigned*)(lds + (bufoff) + ldsw + _i * 8192), 16, 0, 0); } while (0)
; #define PG8_LDA(dst, b, h) do { _Pragma("unroll") for (int m = 0; m < 4; ++m) _Pragma("unroll") for (int k = 0; k < 2; ++k) dst[m][k] = *(const LAS bf16x8*)(lds + PG8_SA(b, h) + aoff + m * 2048 + k * 1024); } while (0)
; #define PG8_MMA(ai, bj, At, Bt) do { __builtin_amdgcn_s_setprio(1); _Pragma("unroll") for (int m = 0; m < 4; ++m) _Pragma("unroll") for (int n = 0; n < 2; ++n) _Pragma("unroll") for (int k = 0; k < 2; ++k) \
;         acc[ai][bj][m][n] = __builtin_amdgcn_mfma_f32_16x16x32_bf16(Bt[n][k], At[m][k], acc[ai][bj][m][n], 0, 0, 0); __builtin_amdgcn_s_setprio(0); } while (0)
; #define PG8_WAIT_V(n) asm volatile("s_waitcnt vmcnt(" #n ")" ::: "memory")
; #define PG8_WAIT_L(n) asm volatile("s_waitcnt lgkmcnt(" #n ")" ::: "memory")
; #define PG8_BAR __builtin_amdgcn_s_barrier()
; #define PG8_SCHED __builtin_amdgcn_sched_barrier(0)
; template <class Epi, class Sched>
; __device__ __forceinline__ void gemm_phase(LAS unsigned char* lds, const Gemm g, const Sched& S, const Epi& E) {
;     ...
;             PG8_LDA(At, 1, 1); PG8_STAGE(PG8_SB(1, 0), b3, voffB); PG8_STAGE(PG8_SB(1, 1), b3 + hstepB, voffB); PG8_STAGE(PG8_SA(1, 0), a3, voffA);
;             PG8_WAIT_V(8); PG8_WAIT_L(0); PG8_BAR; PG8_MMA(1, 0, At, B0); PG8_MMA(1, 1, At, B1); PG8_BAR; PG8_SCHED;
;         }
;         if (wr == 0) PG8_BAR;
	s_add_i32 s0, s0, s20
	v_lshl_add_u64 v[158:159], v[158:159], 0, s[30:31]
	s_mov_b32 m0, s0
	ds_read_b128 v[200:203], v152 offset:49152
	ds_read_b128 v[204:207], v152 offset:50176
	ds_read_b128 v[208:211], v152 offset:51200
	ds_read_b128 v[212:215], v152 offset:52224
	ds_read_b128 v[216:219], v152 offset:53248
	ds_read_b128 v[220:223], v152 offset:54272
	ds_read_b128 v[224:227], v152 offset:55296
	ds_read_b128 v[228:231], v152 offset:56320
	global_load_lds_dwordx4 v[158:159], off
	s_add_i32 m0, s0, 0x2000
	s_add_u32 s6, s6, 0x40080
	v_lshl_add_u64 v[158:159], v[232:233], 0, s[30:31]
	s_addc_u32 s7, s7, 0
	s_add_i32 s0, s26, s20
	global_load_lds_dwordx4 v[158:159], off
	v_lshl_add_u64 v[158:159], s[6:7], 0, v[160:161]
	s_mov_b32 m0, s0
	s_nop 0
	global_load_lds_dwordx4 v[158:159], off
	v_lshl_add_u64 v[158:159], s[6:7], 0, v[136:137]
	s_add_i32 m0, s0, 0x2000
	s_nop 0
	global_load_lds_dwordx4 v[158:159], off
	v_lshl_add_u64 v[232:233], v[234:235], 0, s[30:31]
	v_lshl_add_u64 v[158:159], v[236:237], 0, s[30:31]
	s_waitcnt vmcnt(6)
	s_waitcnt lgkmcnt(0)
	s_barrier
	s_waitcnt lgkmcnt(0)
	v_mfma_f32_16x16x32_bf16 v[64:67], v[142:145], v[200:203], v[64:67]
	v_mfma_f32_16x16x32_bf16 v[60:63], v[162:165], v[200:203], v[60:63]
	v_mfma_f32_16x16x32_bf16 v[48:51], v[142:145], v[208:211], v[48:51]
	v_mfma_f32_16x16x32_bf16 v[44:47], v[162:165], v[208:211], v[44:47]
	v_mfma_f32_16x16x32_bf16 v[32:35], v[142:145], v[216:219], v[32:35]
	v_mfma_f32_16x16x32_bf16 v[28:31], v[162:165], v[216:219], v[28:31]
	v_mfma_f32_16x16x32_bf16 v[16:19], v[142:145], v[224:227], v[16:19]
	v_mfma_f32_16x16x32_bf16 v[12:15], v[162:165], v[224:227], v[12:15]
	v_mfma_f32_16x16x32_bf16 v[64:67], v[154:157], v[204:207], v[64:67]
	v_mfma_f32_16x16x32_bf16 v[60:63], v[166:169], v[204:207], v[60:63]
	v_mfma_f32_16x16x32_bf16 v[48:51], v[154:157], v[212:215], v[48:51]
	v_mfma_f32_16x16x32_bf16 v[44:47], v[166:169], v[212:215], v[44:47]
	v_mfma_f32_16x16x32_bf16 v[32:35], v[154:157], v[220:223], v[32:35]
	v_mfma_f32_16x16x32_bf16 v[28:31], v[166:169], v[220:223], v[28:31]
	v_mfma_f32_16x16x32_bf16 v[16:19], v[154:157], v[228:231], v[16:19]
	v_mfma_f32_16x16x32_bf16 v[12:15], v[166:169], v[228:231], v[12:15]
	s_mov_b32 m0, s24
	s_nop 0
	global_load_lds_dwordx4 v[232:233], off
	s_mov_b32 m0, s25
	s_nop 0
	global_load_lds_dwordx4 v[158:159], off
	v_mfma_f32_16x16x32_bf16 v[56:59], v[170:173], v[200:203], v[56:59]
	v_mfma_f32_16x16x32_bf16 v[52:55], v[190:193], v[200:203], v[52:55]
	v_mfma_f32_16x16x32_bf16 v[40:43], v[170:173], v[208:211], v[40:43]
	v_mfma_f32_16x16x32_bf16 v[36:39], v[190:193], v[208:211], v[36:39]
	v_mfma_f32_16x16x32_bf16 v[24:27], v[170:173], v[216:219], v[24:27]
	v_mfma_f32_16x16x32_bf16 v[20:23], v[190:193], v[216:219], v[20:23]
	v_mfma_f32_16x16x32_bf16 v[8:11], v[170:173], v[224:227], v[8:11]
	v_mfma_f32_16x16x32_bf16 v[4:7], v[190:193], v[224:227], v[4:7]
	v_mfma_f32_16x16x32_bf16 v[56:59], v[174:177], v[204:207], v[56:59]
	v_mfma_f32_16x16x32_bf16 v[52:55], v[196:199], v[204:207], v[52:55]
	v_mfma_f32_16x16x32_bf16 v[40:43], v[174:177], v[212:215], v[40:43]
	v_mfma_f32_16x16x32_bf16 v[36:39], v[196:199], v[212:215], v[36:39]
	v_mfma_f32_16x16x32_bf16 v[24:27], v[174:177], v[220:223], v[24:27]
	v_mfma_f32_16x16x32_bf16 v[20:23], v[196:199], v[220:223], v[20:23]
	v_mfma_f32_16x16x32_bf16 v[8:11], v[174:177], v[228:231], v[8:11]
	v_mfma_f32_16x16x32_bf16 v[4:7], v[196:199], v[228:231], v[4:7]
	s_barrier
	s_add_i32 s55, s55, 2
	s_add_u32 s44, s44, 0x100
	s_addc_u32 s45, s45, 0
	s_add_u32 s46, s46, 0x100
	s_addc_u32 s47, s47, 0
	s_cmp_gt_u32 s55, 13
	s_cbranch_scc0 .LBB0_718
	s_and_b64 vcc, exec, s[16:17]
	s_cbranch_vccz .LBB0_721
	s_barrier
